# v111 + next-item work-queue prefetch in the gate FOR_ITEMS phase (thread 0 issues the atomic at item start, consumed at the next pull)
# baseline (speedup 1.0000x reference)
.LBB0_874:
	s_lshl_b32 s42, s64, 3
	s_ashr_i32 s43, s42, 31
	s_lshl_b64 s[0:1], s[42:43], 2
	v_readlane_b32 s40, v252, 55
	v_readlane_b32 s41, v252, 56
	s_add_u32 s0, s40, s0
	s_addc_u32 s1, s41, s1
	v_readlane_b32 s40, v254, 63
	v_readlane_b32 s41, v255, 0
	s_mov_b32 s41, s35
	s_lshl_b64 s[40:41], s[40:41], 2
	s_add_u32 s44, s14, s40
	v_readlane_b32 s48, v252, 0
	s_addc_u32 s45, s15, s41
	v_readlane_b32 s62, v252, 14
	v_readlane_b32 s40, v255, 1
	v_readlane_b32 s63, v252, 15
	v_readlane_b32 s41, v255, 2
	s_add_u32 s46, s62, s40
	s_addc_u32 s47, s63, s41
	s_waitcnt lgkmcnt(0)
	v_readlane_b32 s49, v252, 1
	v_readlane_b32 s50, v252, 2
	v_readlane_b32 s51, v252, 3
	v_readlane_b32 s52, v252, 4
	v_readlane_b32 s53, v252, 5
	v_readlane_b32 s54, v252, 6
	v_readlane_b32 s55, v252, 7
	v_readlane_b32 s56, v252, 8
	v_readlane_b32 s57, v252, 9
	v_readlane_b32 s58, v252, 10
	v_readlane_b32 s59, v252, 11
	v_readlane_b32 s60, v252, 12
	v_readlane_b32 s61, v252, 13
	s_mov_b32 s99, 0
	s_branch .LBB0_876

.LBB0_876:
	s_barrier
	s_mov_b64 s[40:41], exec
	v_readlane_b32 s48, v252, 21
	v_readlane_b32 s49, v252, 22
	s_and_b64 s[48:49], s[40:41], s[48:49]
	s_mov_b64 exec, s[48:49]
	s_cbranch_execz .LBB0_880
	s_mov_b64 s[50:51], exec
	v_mbcnt_lo_u32_b32 v0, s50, 0
	v_mbcnt_hi_u32_b32 v0, s51, v0
	v_cmp_eq_u32_e32 vcc, 0, v0
	s_and_saveexec_b64 s[48:49], vcc
	s_cbranch_execz .LBB0_879
	s_cmp_eq_u32 s99, 1
	s_cbranch_scc0 .Lgp_none
	s_mov_b32 s99, 0
	s_waitcnt vmcnt(0)
	v_mov_b32_e32 v1, v248
	s_branch .LBB0_879
.Lgp_none:
	s_bcnt1_i32_b64 s25, s[50:51]
	v_mov_b32_e32 v1, s25
	global_atomic_add v1, v17, v1, s[0:1] sc0

.LBB0_880:
	s_or_b64 exec, exec, s[40:41]
	s_waitcnt lgkmcnt(0)
	s_barrier
	ds_read_b32 v0, v230
	s_movk_i32 s25, 0x47f
	s_waitcnt lgkmcnt(0)
	v_cmp_lt_i32_e64 s[40:41], s25, v0
	v_readfirstlane_b32 s25, v0
	v_lshl_add_u32 v1, v0, 1, v216
	s_cmpk_lt_i32 s25, 0x480
	s_movk_i32 s25, 0x900
	s_cselect_b64 s[48:49], -1, 0
	v_cmp_gt_i32_e32 vcc, s25, v1
	s_and_b64 s[50:51], s[48:49], vcc
	s_and_saveexec_b64 s[48:49], s[50:51]
	s_cbranch_execz .LBB0_875
	s_waitcnt vmcnt(1)
	v_readfirstlane_b32 s99, v195
	s_cmp_lg_u32 s99, 0
	s_mov_b32 s99, 0
	s_cbranch_scc1 .Lgp_skip
	s_mov_b64 s[100:101], exec
	s_mov_b64 exec, 1
	global_atomic_add v248, v17, v229, s[0:1] sc0
	s_mov_b64 exec, s[100:101]
	s_mov_b32 s99, 1
.Lgp_skip:
	v_mov_b32_e32 v2, v217
	v_lshlrev_b32_e32 v0, 5, v0
	v_ashrrev_i32_e32 v3, 4, v2
	v_and_b32_e32 v7, -4, v3
	v_lshl_add_u32 v43, v1, 4, v7
	v_bfe_u32 v1, v2, 3, 3
	v_readlane_b32 s25, v255, 4
	v_add3_u32 v0, v228, v0, v7
	v_and_b32_e32 v6, 63, v2
	v_or_b32_e32 v2, s25, v1
	v_mad_i64_i32 v[0:1], s[50:51], v0, s33, 0
	v_mov_b32_e32 v3, v17
	v_readlane_b32 s50, v252, 19
	v_lshlrev_b32_e32 v16, 3, v6
	v_lshlrev_b32_e32 v4, 4, v6
	v_mov_b32_e32 v5, v17
	v_lshl_add_u64 v[28:29], v[2:3], 2, s[12:13]
	v_lshlrev_b32_e32 v2, 5, v6
	v_lshl_or_b32 v0, v6, 2, v0
	v_readlane_b32 s51, v252, 20
	v_lshl_add_u64 v[26:27], s[6:7], 0, v[4:5]
	v_lshl_add_u64 v[30:31], s[44:45], 0, v[2:3]
	v_lshl_add_u64 v[32:33], s[46:47], 0, v[16:17]
	v_lshl_add_u64 v[34:35], s[50:51], 0, v[0:1]
	s_mov_b32 s25, 0
	v_lshlrev_b32_e32 v16, 1, v16
	s_and_b64 vcc, exec, s[10:11]
	s_cbranch_vccnz .LBB0_883
	v_and_b32_e32 v110, 15, v6
	v_lshlrev_b32_e32 v110, 5, v110
	global_load_dwordx4 v[114:117], v110, s[46:47] offset:16
	global_load_dwordx4 v[110:113], v110, s[46:47]
	v_mul_u32_u24_e32 v102, 12, v6
	v_mov_b32_e32 v103, 0
	s_mov_b64 s[52:53], 0xa921000
	v_lshl_add_u64 v[102:103], v[34:35], 0, v[102:103]
	v_lshl_add_u64 v[102:103], v[102:103], 0, s[52:53]
	s_mov_b64 s[52:53], 0x1800
	v_lshl_add_u64 v[104:105], v[102:103], 0, s[52:53]
	v_lshl_add_u64 v[106:107], v[104:105], 0, s[52:53]
	v_lshl_add_u64 v[108:109], v[106:107], 0, s[52:53]
	global_load_dwordx4 v[54:57], v[102:103], off
	global_load_dwordx4 v[58:61], v[102:103], off offset:1024
	global_load_dwordx4 v[62:65], v[102:103], off offset:3072
	global_load_dwordx4 v[66:69], v[104:105], off
	global_load_dwordx4 v[70:73], v[104:105], off offset:1024
	global_load_dwordx4 v[74:77], v[104:105], off offset:3072
	global_load_dwordx4 v[78:81], v[106:107], off
	global_load_dwordx4 v[82:85], v[106:107], off offset:1024
	global_load_dwordx4 v[86:89], v[106:107], off offset:3072
	global_load_dwordx4 v[90:93], v[108:109], off
	global_load_dwordx4 v[94:97], v[108:109], off offset:1024
	global_load_dwordx4 v[98:101], v[108:109], off offset:3072
	s_waitcnt vmcnt(9)
	v_lshlrev_b32_e32 v118, 16, v54
	v_lshlrev_b32_e32 v119, 16, v58
	v_and_b32_e32 v54, 0xffff0000, v54
	v_and_b32_e32 v120, 0xffff0000, v58
	v_add_f32_e32 v58, v118, v119
	v_add_f32_e32 v54, v54, v120
	v_lshlrev_b32_e32 v118, 16, v55
	v_lshlrev_b32_e32 v119, 16, v59
	v_and_b32_e32 v55, 0xffff0000, v55
	v_and_b32_e32 v120, 0xffff0000, v59
	v_add_f32_e32 v59, v118, v119
	v_add_f32_e32 v55, v55, v120
	v_lshlrev_b32_e32 v118, 16, v56
	v_lshlrev_b32_e32 v119, 16, v60
	v_and_b32_e32 v56, 0xffff0000, v56
	v_and_b32_e32 v120, 0xffff0000, v60
	v_add_f32_e32 v60, v118, v119
	v_add_f32_e32 v56, v56, v120
	v_lshlrev_b32_e32 v118, 16, v57
	v_lshlrev_b32_e32 v119, 16, v61
	v_and_b32_e32 v57, 0xffff0000, v57
	v_and_b32_e32 v120, 0xffff0000, v61
	v_add_f32_e32 v61, v118, v119
	v_add_f32_e32 v57, v57, v120
	v_mul_f32_e32 v118, v58, v58
	v_fmac_f32_e32 v118, v54, v54
	v_fmac_f32_e32 v118, v59, v59
	v_fmac_f32_e32 v118, v55, v55
	v_fmac_f32_e32 v118, v60, v60
	v_fmac_f32_e32 v118, v56, v56
	v_fmac_f32_e32 v118, v61, v61
	v_fmac_f32_e32 v118, v57, v57
	s_nop 1
	v_add_f32_dpp v119, v118, v118 row_ror:8 row_mask:0xf bank_mask:0xf
	s_nop 1
	v_add_f32_dpp v118, v119, v119 row_ror:4 row_mask:0xf bank_mask:0xf
	s_nop 1
	v_add_f32_dpp v119, v118, v118 row_ror:2 row_mask:0xf bank_mask:0xf
	s_nop 1
	v_add_f32_dpp v118, v119, v119 row_ror:1 row_mask:0xf bank_mask:0xf
	s_nop 0
	v_fmamk_f32 v118, v118, 0x3c000000, v231
	v_cmp_gt_f32_e32 vcc, s3, v118
	v_mul_f32_e32 v119, 0x4b800000, v118
	s_nop 0
	v_cndmask_b32_e32 v118, v118, v119, vcc
	v_rsq_f32_e32 v118, v118
	s_nop 0
	v_mul_f32_e32 v119, 0x45800000, v118
	v_cndmask_b32_e32 v118, v118, v119, vcc
	v_lshlrev_b32_e32 v119, 16, v62
	v_and_b32_e32 v120, 0xffff0000, v62
	v_mul_f32_e32 v121, 0xbfb8aa3b, v119
	v_mul_f32_e32 v122, 0xbfb8aa3b, v120
	v_mul_f32_e32 v58, v58, v118
	v_mul_f32_e32 v54, v54, v118
	v_exp_f32_e32 v121, v121
	v_exp_f32_e32 v122, v122
	v_mul_f32_e32 v58, v110, v58
	v_mul_f32_e32 v54, v111, v54
	v_add_f32_e32 v121, 1.0, v121
	v_add_f32_e32 v122, 1.0, v122
	s_nop 0
	v_rcp_f32_e32 v121, v121
	v_rcp_f32_e32 v122, v122
	s_nop 0
	v_mul_f32_e32 v119, v119, v121
	v_mul_f32_e32 v120, v120, v122
	v_mul_f32_e32 v58, v119, v58
	v_mul_f32_e32 v54, v120, v54
	v_cvt_pk_bf16_f32 v62, v58, v54
	v_lshlrev_b32_e32 v119, 16, v63
	v_and_b32_e32 v120, 0xffff0000, v63
	v_mul_f32_e32 v121, 0xbfb8aa3b, v119
	v_mul_f32_e32 v122, 0xbfb8aa3b, v120
	v_mul_f32_e32 v59, v59, v118
	v_mul_f32_e32 v55, v55, v118
	v_exp_f32_e32 v121, v121
	v_exp_f32_e32 v122, v122
	v_mul_f32_e32 v59, v112, v59
	v_mul_f32_e32 v55, v113, v55
	v_add_f32_e32 v121, 1.0, v121
	v_add_f32_e32 v122, 1.0, v122
	s_nop 0
	v_rcp_f32_e32 v121, v121
	v_rcp_f32_e32 v122, v122
	s_nop 0
	v_mul_f32_e32 v119, v119, v121
	v_mul_f32_e32 v120, v120, v122
	v_mul_f32_e32 v59, v119, v59
	v_mul_f32_e32 v55, v120, v55
	v_cvt_pk_bf16_f32 v63, v59, v55
	v_lshlrev_b32_e32 v119, 16, v64
	v_and_b32_e32 v120, 0xffff0000, v64
	v_mul_f32_e32 v121, 0xbfb8aa3b, v119
	v_mul_f32_e32 v122, 0xbfb8aa3b, v120
	v_mul_f32_e32 v60, v60, v118
	v_mul_f32_e32 v56, v56, v118
	v_exp_f32_e32 v121, v121
	v_exp_f32_e32 v122, v122
	v_mul_f32_e32 v60, v114, v60
	v_mul_f32_e32 v56, v115, v56
	v_add_f32_e32 v121, 1.0, v121
	v_add_f32_e32 v122, 1.0, v122
	s_nop 0
	v_rcp_f32_e32 v121, v121
	v_rcp_f32_e32 v122, v122
	s_nop 0
	v_mul_f32_e32 v119, v119, v121
	v_mul_f32_e32 v120, v120, v122
	v_mul_f32_e32 v60, v119, v60
	v_mul_f32_e32 v56, v120, v56
	v_cvt_pk_bf16_f32 v64, v60, v56
	v_lshlrev_b32_e32 v119, 16, v65
	v_and_b32_e32 v120, 0xffff0000, v65
	v_mul_f32_e32 v121, 0xbfb8aa3b, v119
	v_mul_f32_e32 v122, 0xbfb8aa3b, v120
	v_mul_f32_e32 v61, v61, v118
	v_mul_f32_e32 v57, v57, v118
	v_exp_f32_e32 v121, v121
	v_exp_f32_e32 v122, v122
	v_mul_f32_e32 v61, v116, v61
	v_mul_f32_e32 v57, v117, v57
	v_add_f32_e32 v121, 1.0, v121
	v_add_f32_e32 v122, 1.0, v122
	s_nop 0
	v_rcp_f32_e32 v121, v121
	v_rcp_f32_e32 v122, v122
	s_nop 0
	v_mul_f32_e32 v119, v119, v121
	v_mul_f32_e32 v120, v120, v122
	v_mul_f32_e32 v61, v119, v61
	v_mul_f32_e32 v57, v120, v57
	v_cvt_pk_bf16_f32 v65, v61, v57
	global_store_dwordx4 v[102:103], v[62:65], off
	s_waitcnt vmcnt(7)
	v_lshlrev_b32_e32 v118, 16, v66
	v_lshlrev_b32_e32 v119, 16, v70
	v_and_b32_e32 v66, 0xffff0000, v66
	v_and_b32_e32 v120, 0xffff0000, v70
	v_add_f32_e32 v70, v118, v119
	v_add_f32_e32 v66, v66, v120
	v_lshlrev_b32_e32 v118, 16, v67
	v_lshlrev_b32_e32 v119, 16, v71
	v_and_b32_e32 v67, 0xffff0000, v67
	v_and_b32_e32 v120, 0xffff0000, v71
	v_add_f32_e32 v71, v118, v119
	v_add_f32_e32 v67, v67, v120
	v_lshlrev_b32_e32 v118, 16, v68
	v_lshlrev_b32_e32 v119, 16, v72
	v_and_b32_e32 v68, 0xffff0000, v68
	v_and_b32_e32 v120, 0xffff0000, v72
	v_add_f32_e32 v72, v118, v119
	v_add_f32_e32 v68, v68, v120
	v_lshlrev_b32_e32 v118, 16, v69
	v_lshlrev_b32_e32 v119, 16, v73
	v_and_b32_e32 v69, 0xffff0000, v69
	v_and_b32_e32 v120, 0xffff0000, v73
	v_add_f32_e32 v73, v118, v119
	v_add_f32_e32 v69, v69, v120
	v_mul_f32_e32 v118, v70, v70
	v_fmac_f32_e32 v118, v66, v66
	v_fmac_f32_e32 v118, v71, v71
	v_fmac_f32_e32 v118, v67, v67
	v_fmac_f32_e32 v118, v72, v72
	v_fmac_f32_e32 v118, v68, v68
	v_fmac_f32_e32 v118, v73, v73
	v_fmac_f32_e32 v118, v69, v69
	s_nop 1
	v_add_f32_dpp v119, v118, v118 row_ror:8 row_mask:0xf bank_mask:0xf
	s_nop 1
	v_add_f32_dpp v118, v119, v119 row_ror:4 row_mask:0xf bank_mask:0xf
	s_nop 1
	v_add_f32_dpp v119, v118, v118 row_ror:2 row_mask:0xf bank_mask:0xf
	s_nop 1
	v_add_f32_dpp v118, v119, v119 row_ror:1 row_mask:0xf bank_mask:0xf
	s_nop 0
	v_fmamk_f32 v118, v118, 0x3c000000, v231
	v_cmp_gt_f32_e32 vcc, s3, v118
	v_mul_f32_e32 v119, 0x4b800000, v118
	s_nop 0
	v_cndmask_b32_e32 v118, v118, v119, vcc
	v_rsq_f32_e32 v118, v118
	s_nop 0
	v_mul_f32_e32 v119, 0x45800000, v118
	v_cndmask_b32_e32 v118, v118, v119, vcc
	v_lshlrev_b32_e32 v119, 16, v74
	v_and_b32_e32 v120, 0xffff0000, v74
	v_mul_f32_e32 v121, 0xbfb8aa3b, v119
	v_mul_f32_e32 v122, 0xbfb8aa3b, v120
	v_mul_f32_e32 v70, v70, v118
	v_mul_f32_e32 v66, v66, v118
	v_exp_f32_e32 v121, v121
	v_exp_f32_e32 v122, v122
	v_mul_f32_e32 v70, v110, v70
	v_mul_f32_e32 v66, v111, v66
	v_add_f32_e32 v121, 1.0, v121
	v_add_f32_e32 v122, 1.0, v122
	s_nop 0
	v_rcp_f32_e32 v121, v121
	v_rcp_f32_e32 v122, v122
	s_nop 0
	v_mul_f32_e32 v119, v119, v121
	v_mul_f32_e32 v120, v120, v122
	v_mul_f32_e32 v70, v119, v70
	v_mul_f32_e32 v66, v120, v66
	v_cvt_pk_bf16_f32 v74, v70, v66
	v_lshlrev_b32_e32 v119, 16, v75
	v_and_b32_e32 v120, 0xffff0000, v75
	v_mul_f32_e32 v121, 0xbfb8aa3b, v119
	v_mul_f32_e32 v122, 0xbfb8aa3b, v120
	v_mul_f32_e32 v71, v71, v118
	v_mul_f32_e32 v67, v67, v118
	v_exp_f32_e32 v121, v121
	v_exp_f32_e32 v122, v122
	v_mul_f32_e32 v71, v112, v71
	v_mul_f32_e32 v67, v113, v67
	v_add_f32_e32 v121, 1.0, v121
	v_add_f32_e32 v122, 1.0, v122
	s_nop 0
	v_rcp_f32_e32 v121, v121
	v_rcp_f32_e32 v122, v122
	s_nop 0
	v_mul_f32_e32 v119, v119, v121
	v_mul_f32_e32 v120, v120, v122
	v_mul_f32_e32 v71, v119, v71
	v_mul_f32_e32 v67, v120, v67
	v_cvt_pk_bf16_f32 v75, v71, v67
	v_lshlrev_b32_e32 v119, 16, v76
	v_and_b32_e32 v120, 0xffff0000, v76
	v_mul_f32_e32 v121, 0xbfb8aa3b, v119
	v_mul_f32_e32 v122, 0xbfb8aa3b, v120
	v_mul_f32_e32 v72, v72, v118
	v_mul_f32_e32 v68, v68, v118
	v_exp_f32_e32 v121, v121
	v_exp_f32_e32 v122, v122
	v_mul_f32_e32 v72, v114, v72
	v_mul_f32_e32 v68, v115, v68
	v_add_f32_e32 v121, 1.0, v121
	v_add_f32_e32 v122, 1.0, v122
	s_nop 0
	v_rcp_f32_e32 v121, v121
	v_rcp_f32_e32 v122, v122
	s_nop 0
	v_mul_f32_e32 v119, v119, v121
	v_mul_f32_e32 v120, v120, v122
	v_mul_f32_e32 v72, v119, v72
	v_mul_f32_e32 v68, v120, v68
	v_cvt_pk_bf16_f32 v76, v72, v68
	v_lshlrev_b32_e32 v119, 16, v77
	v_and_b32_e32 v120, 0xffff0000, v77
	v_mul_f32_e32 v121, 0xbfb8aa3b, v119
	v_mul_f32_e32 v122, 0xbfb8aa3b, v120
	v_mul_f32_e32 v73, v73, v118
	v_mul_f32_e32 v69, v69, v118
	v_exp_f32_e32 v121, v121
	v_exp_f32_e32 v122, v122
	v_mul_f32_e32 v73, v116, v73
	v_mul_f32_e32 v69, v117, v69
	v_add_f32_e32 v121, 1.0, v121
	v_add_f32_e32 v122, 1.0, v122
	s_nop 0
	v_rcp_f32_e32 v121, v121
	v_rcp_f32_e32 v122, v122
	s_nop 0
	v_mul_f32_e32 v119, v119, v121
	v_mul_f32_e32 v120, v120, v122
	v_mul_f32_e32 v73, v119, v73
	v_mul_f32_e32 v69, v120, v69
	v_cvt_pk_bf16_f32 v77, v73, v69
	global_store_dwordx4 v[104:105], v[74:77], off
	s_waitcnt vmcnt(5)
	v_lshlrev_b32_e32 v118, 16, v78
	v_lshlrev_b32_e32 v119, 16, v82
	v_and_b32_e32 v78, 0xffff0000, v78
	v_and_b32_e32 v120, 0xffff0000, v82
	v_add_f32_e32 v82, v118, v119
	v_add_f32_e32 v78, v78, v120
	v_lshlrev_b32_e32 v118, 16, v79
	v_lshlrev_b32_e32 v119, 16, v83
	v_and_b32_e32 v79, 0xffff0000, v79
	v_and_b32_e32 v120, 0xffff0000, v83
	v_add_f32_e32 v83, v118, v119
	v_add_f32_e32 v79, v79, v120
	v_lshlrev_b32_e32 v118, 16, v80
	v_lshlrev_b32_e32 v119, 16, v84
	v_and_b32_e32 v80, 0xffff0000, v80
	v_and_b32_e32 v120, 0xffff0000, v84
	v_add_f32_e32 v84, v118, v119
	v_add_f32_e32 v80, v80, v120
	v_lshlrev_b32_e32 v118, 16, v81
	v_lshlrev_b32_e32 v119, 16, v85
	v_and_b32_e32 v81, 0xffff0000, v81
	v_and_b32_e32 v120, 0xffff0000, v85
	v_add_f32_e32 v85, v118, v119
	v_add_f32_e32 v81, v81, v120
	v_mul_f32_e32 v118, v82, v82
	v_fmac_f32_e32 v118, v78, v78
	v_fmac_f32_e32 v118, v83, v83
	v_fmac_f32_e32 v118, v79, v79
	v_fmac_f32_e32 v118, v84, v84
	v_fmac_f32_e32 v118, v80, v80
	v_fmac_f32_e32 v118, v85, v85
	v_fmac_f32_e32 v118, v81, v81
	s_nop 1
	v_add_f32_dpp v119, v118, v118 row_ror:8 row_mask:0xf bank_mask:0xf
	s_nop 1
	v_add_f32_dpp v118, v119, v119 row_ror:4 row_mask:0xf bank_mask:0xf
	s_nop 1
	v_add_f32_dpp v119, v118, v118 row_ror:2 row_mask:0xf bank_mask:0xf
	s_nop 1
	v_add_f32_dpp v118, v119, v119 row_ror:1 row_mask:0xf bank_mask:0xf
	s_nop 0
	v_fmamk_f32 v118, v118, 0x3c000000, v231
	v_cmp_gt_f32_e32 vcc, s3, v118
	v_mul_f32_e32 v119, 0x4b800000, v118
	s_nop 0
	v_cndmask_b32_e32 v118, v118, v119, vcc
	v_rsq_f32_e32 v118, v118
	s_nop 0
	v_mul_f32_e32 v119, 0x45800000, v118
	v_cndmask_b32_e32 v118, v118, v119, vcc
	v_lshlrev_b32_e32 v119, 16, v86
	v_and_b32_e32 v120, 0xffff0000, v86
	v_mul_f32_e32 v121, 0xbfb8aa3b, v119
	v_mul_f32_e32 v122, 0xbfb8aa3b, v120
	v_mul_f32_e32 v82, v82, v118
	v_mul_f32_e32 v78, v78, v118
	v_exp_f32_e32 v121, v121
	v_exp_f32_e32 v122, v122
	v_mul_f32_e32 v82, v110, v82
	v_mul_f32_e32 v78, v111, v78
	v_add_f32_e32 v121, 1.0, v121
	v_add_f32_e32 v122, 1.0, v122
	s_nop 0
	v_rcp_f32_e32 v121, v121
	v_rcp_f32_e32 v122, v122
	s_nop 0
	v_mul_f32_e32 v119, v119, v121
	v_mul_f32_e32 v120, v120, v122
	v_mul_f32_e32 v82, v119, v82
	v_mul_f32_e32 v78, v120, v78
	v_cvt_pk_bf16_f32 v86, v82, v78
	v_lshlrev_b32_e32 v119, 16, v87
	v_and_b32_e32 v120, 0xffff0000, v87
	v_mul_f32_e32 v121, 0xbfb8aa3b, v119
	v_mul_f32_e32 v122, 0xbfb8aa3b, v120
	v_mul_f32_e32 v83, v83, v118
	v_mul_f32_e32 v79, v79, v118
	v_exp_f32_e32 v121, v121
	v_exp_f32_e32 v122, v122
	v_mul_f32_e32 v83, v112, v83
	v_mul_f32_e32 v79, v113, v79
	v_add_f32_e32 v121, 1.0, v121
	v_add_f32_e32 v122, 1.0, v122
	s_nop 0
	v_rcp_f32_e32 v121, v121
	v_rcp_f32_e32 v122, v122
	s_nop 0
	v_mul_f32_e32 v119, v119, v121
	v_mul_f32_e32 v120, v120, v122
	v_mul_f32_e32 v83, v119, v83
	v_mul_f32_e32 v79, v120, v79
	v_cvt_pk_bf16_f32 v87, v83, v79
	v_lshlrev_b32_e32 v119, 16, v88
	v_and_b32_e32 v120, 0xffff0000, v88
	v_mul_f32_e32 v121, 0xbfb8aa3b, v119
	v_mul_f32_e32 v122, 0xbfb8aa3b, v120
	v_mul_f32_e32 v84, v84, v118
	v_mul_f32_e32 v80, v80, v118
	v_exp_f32_e32 v121, v121
	v_exp_f32_e32 v122, v122
	v_mul_f32_e32 v84, v114, v84
	v_mul_f32_e32 v80, v115, v80
	v_add_f32_e32 v121, 1.0, v121
	v_add_f32_e32 v122, 1.0, v122
	s_nop 0
	v_rcp_f32_e32 v121, v121
	v_rcp_f32_e32 v122, v122
	s_nop 0
	v_mul_f32_e32 v119, v119, v121
	v_mul_f32_e32 v120, v120, v122
	v_mul_f32_e32 v84, v119, v84
	v_mul_f32_e32 v80, v120, v80
	v_cvt_pk_bf16_f32 v88, v84, v80
	v_lshlrev_b32_e32 v119, 16, v89
	v_and_b32_e32 v120, 0xffff0000, v89
	v_mul_f32_e32 v121, 0xbfb8aa3b, v119
	v_mul_f32_e32 v122, 0xbfb8aa3b, v120
	v_mul_f32_e32 v85, v85, v118
	v_mul_f32_e32 v81, v81, v118
	v_exp_f32_e32 v121, v121
	v_exp_f32_e32 v122, v122
	v_mul_f32_e32 v85, v116, v85
	v_mul_f32_e32 v81, v117, v81
	v_add_f32_e32 v121, 1.0, v121
	v_add_f32_e32 v122, 1.0, v122
	s_nop 0
	v_rcp_f32_e32 v121, v121
	v_rcp_f32_e32 v122, v122
	s_nop 0
	v_mul_f32_e32 v119, v119, v121
	v_mul_f32_e32 v120, v120, v122
	v_mul_f32_e32 v85, v119, v85
	v_mul_f32_e32 v81, v120, v81
	v_cvt_pk_bf16_f32 v89, v85, v81
	global_store_dwordx4 v[106:107], v[86:89], off
	s_waitcnt vmcnt(3)
	v_lshlrev_b32_e32 v118, 16, v90
	v_lshlrev_b32_e32 v119, 16, v94
	v_and_b32_e32 v90, 0xffff0000, v90
	v_and_b32_e32 v120, 0xffff0000, v94
	v_add_f32_e32 v94, v118, v119
	v_add_f32_e32 v90, v90, v120
	v_lshlrev_b32_e32 v118, 16, v91
	v_lshlrev_b32_e32 v119, 16, v95
	v_and_b32_e32 v91, 0xffff0000, v91
	v_and_b32_e32 v120, 0xffff0000, v95
	v_add_f32_e32 v95, v118, v119
	v_add_f32_e32 v91, v91, v120
	v_lshlrev_b32_e32 v118, 16, v92
	v_lshlrev_b32_e32 v119, 16, v96
	v_and_b32_e32 v92, 0xffff0000, v92
	v_and_b32_e32 v120, 0xffff0000, v96
	v_add_f32_e32 v96, v118, v119
	v_add_f32_e32 v92, v92, v120
	v_lshlrev_b32_e32 v118, 16, v93
	v_lshlrev_b32_e32 v119, 16, v97
	v_and_b32_e32 v93, 0xffff0000, v93
	v_and_b32_e32 v120, 0xffff0000, v97
	v_add_f32_e32 v97, v118, v119
	v_add_f32_e32 v93, v93, v120
	v_mul_f32_e32 v118, v94, v94
	v_fmac_f32_e32 v118, v90, v90
	v_fmac_f32_e32 v118, v95, v95
	v_fmac_f32_e32 v118, v91, v91
	v_fmac_f32_e32 v118, v96, v96
	v_fmac_f32_e32 v118, v92, v92
	v_fmac_f32_e32 v118, v97, v97
	v_fmac_f32_e32 v118, v93, v93
	s_nop 1
	v_add_f32_dpp v119, v118, v118 row_ror:8 row_mask:0xf bank_mask:0xf
	s_nop 1
	v_add_f32_dpp v118, v119, v119 row_ror:4 row_mask:0xf bank_mask:0xf
	s_nop 1
	v_add_f32_dpp v119, v118, v118 row_ror:2 row_mask:0xf bank_mask:0xf
	s_nop 1
	v_add_f32_dpp v118, v119, v119 row_ror:1 row_mask:0xf bank_mask:0xf
	s_nop 0
	v_fmamk_f32 v118, v118, 0x3c000000, v231
	v_cmp_gt_f32_e32 vcc, s3, v118
	v_mul_f32_e32 v119, 0x4b800000, v118
	s_nop 0
	v_cndmask_b32_e32 v118, v118, v119, vcc
	v_rsq_f32_e32 v118, v118
	s_nop 0
	v_mul_f32_e32 v119, 0x45800000, v118
	v_cndmask_b32_e32 v118, v118, v119, vcc
	v_lshlrev_b32_e32 v119, 16, v98
	v_and_b32_e32 v120, 0xffff0000, v98
	v_mul_f32_e32 v121, 0xbfb8aa3b, v119
	v_mul_f32_e32 v122, 0xbfb8aa3b, v120
	v_mul_f32_e32 v94, v94, v118
	v_mul_f32_e32 v90, v90, v118
	v_exp_f32_e32 v121, v121
	v_exp_f32_e32 v122, v122
	v_mul_f32_e32 v94, v110, v94
	v_mul_f32_e32 v90, v111, v90
	v_add_f32_e32 v121, 1.0, v121
	v_add_f32_e32 v122, 1.0, v122
	s_nop 0
	v_rcp_f32_e32 v121, v121
	v_rcp_f32_e32 v122, v122
	s_nop 0
	v_mul_f32_e32 v119, v119, v121
	v_mul_f32_e32 v120, v120, v122
	v_mul_f32_e32 v94, v119, v94
	v_mul_f32_e32 v90, v120, v90
	v_cvt_pk_bf16_f32 v98, v94, v90
	v_lshlrev_b32_e32 v119, 16, v99
	v_and_b32_e32 v120, 0xffff0000, v99
	v_mul_f32_e32 v121, 0xbfb8aa3b, v119
	v_mul_f32_e32 v122, 0xbfb8aa3b, v120
	v_mul_f32_e32 v95, v95, v118
	v_mul_f32_e32 v91, v91, v118
	v_exp_f32_e32 v121, v121
	v_exp_f32_e32 v122, v122
	v_mul_f32_e32 v95, v112, v95
	v_mul_f32_e32 v91, v113, v91
	v_add_f32_e32 v121, 1.0, v121
	v_add_f32_e32 v122, 1.0, v122
	s_nop 0
	v_rcp_f32_e32 v121, v121
	v_rcp_f32_e32 v122, v122
	s_nop 0
	v_mul_f32_e32 v119, v119, v121
	v_mul_f32_e32 v120, v120, v122
	v_mul_f32_e32 v95, v119, v95
	v_mul_f32_e32 v91, v120, v91
	v_cvt_pk_bf16_f32 v99, v95, v91
	v_lshlrev_b32_e32 v119, 16, v100
	v_and_b32_e32 v120, 0xffff0000, v100
	v_mul_f32_e32 v121, 0xbfb8aa3b, v119
	v_mul_f32_e32 v122, 0xbfb8aa3b, v120
	v_mul_f32_e32 v96, v96, v118
	v_mul_f32_e32 v92, v92, v118
	v_exp_f32_e32 v121, v121
	v_exp_f32_e32 v122, v122
	v_mul_f32_e32 v96, v114, v96
	v_mul_f32_e32 v92, v115, v92
	v_add_f32_e32 v121, 1.0, v121
	v_add_f32_e32 v122, 1.0, v122
	s_nop 0
	v_rcp_f32_e32 v121, v121
	v_rcp_f32_e32 v122, v122
	s_nop 0
	v_mul_f32_e32 v119, v119, v121
	v_mul_f32_e32 v120, v120, v122
	v_mul_f32_e32 v96, v119, v96
	v_mul_f32_e32 v92, v120, v92
	v_cvt_pk_bf16_f32 v100, v96, v92
	v_lshlrev_b32_e32 v119, 16, v101
	v_and_b32_e32 v120, 0xffff0000, v101
	v_mul_f32_e32 v121, 0xbfb8aa3b, v119
	v_mul_f32_e32 v122, 0xbfb8aa3b, v120
	v_mul_f32_e32 v97, v97, v118
	v_mul_f32_e32 v93, v93, v118
	v_exp_f32_e32 v121, v121
	v_exp_f32_e32 v122, v122
	v_mul_f32_e32 v97, v116, v97
	v_mul_f32_e32 v93, v117, v93
	v_add_f32_e32 v121, 1.0, v121
	v_add_f32_e32 v122, 1.0, v122
	s_nop 0
	v_rcp_f32_e32 v121, v121
	v_rcp_f32_e32 v122, v122
	s_nop 0
	v_mul_f32_e32 v119, v119, v121
	v_mul_f32_e32 v120, v120, v122
	v_mul_f32_e32 v97, v119, v97
	v_mul_f32_e32 v93, v120, v93
	v_cvt_pk_bf16_f32 v101, v97, v93
	global_store_dwordx4 v[108:109], v[98:101], off
	s_branch .LBB0_875
	s_branch .LBB0_883
